# speedup vs baseline: 1.1099x; 1.0003x over previous
; template <int MASK>
; __global__ void __launch_bounds__(256, 2) fwd_megakernel_t(Params p) {
;     ...
; #pragma unroll 1
;         for (int k = 0; k < 128; k += 4) {
;           const int idv = (k & 64) ? idhi : idlo;
;           uint4 r[4][2];
; #pragma unroll
;           for (int e = 0; e < 4; e++) {
;             const int id = __builtin_amdgcn_readlane(idv, (k & 63) + e);
;             const unsigned char* ur = peu + (size_t)id * 2048 + lane * 16;
;             r[e][0] = *(const uint4*)ur;
;             r[e][1] = *(const uint4*)(ur + 1024);
;           }
;           float a[4];
; #pragma unroll
;           for (int e = 0; e < 4; e++) {
;             float s0 = 0.f, s1 = 0.f;
;             s0 = dot4_fp8(r[e][0].x, xn[0], xn[1], xn[2], xn[3], s0);
;             s1 = dot4_fp8(r[e][0].y, xn[4], xn[5], xn[6], xn[7], s1);
;             s0 = dot4_fp8(r[e][0].z, xn[8], xn[9], xn[10], xn[11], s0);
;             s1 = dot4_fp8(r[e][0].w, xn[12], xn[13], xn[14], xn[15], s1);
;             s0 = dot4_fp8(r[e][1].x, xn[16], xn[17], xn[18], xn[19], s0);
;             s1 = dot4_fp8(r[e][1].y, xn[20], xn[21], xn[22], xn[23], s1);
;             s0 = dot4_fp8(r[e][1].z, xn[24], xn[25], xn[26], xn[27], s0);
;             s1 = dot4_fp8(r[e][1].w, xn[28], xn[29], xn[30], xn[31], s1);
;             a[e] = s0 + s1;
;           }
.LBB0_37:
	s_cmp_lt_u32 s22, 64
	s_cselect_b64 vcc, -1, 0
	s_waitcnt vmcnt(0)
	v_cndmask_b32_e32 v2, v62, v29, vcc
	s_nop 0
	v_readlane_b32 s12, v2, s22
	s_ashr_i32 s13, s12, 31
	s_lshl_b64 s[12:13], s[12:13], 11
	s_waitcnt lgkmcnt(0)
	v_lshl_add_u64 v[0:1], v[32:33], 0, s[12:13]
	global_load_dwordx4 v[94:97], v[0:1], off
	global_load_dwordx4 v[24:27], v[0:1], off offset:1024
	s_add_i32 s12, s22, 1
	v_readlane_b32 s12, v2, s12
	s_ashr_i32 s13, s12, 31
	s_lshl_b64 s[12:13], s[12:13], 11
	v_lshl_add_u64 v[0:1], v[32:33], 0, s[12:13]
	global_load_dwordx4 v[20:23], v[0:1], off
	global_load_dwordx4 v[16:19], v[0:1], off offset:1024
	s_add_i32 s12, s22, 2
	v_readlane_b32 s12, v2, s12
	s_ashr_i32 s13, s12, 31
	s_lshl_b64 s[12:13], s[12:13], 11
	v_lshl_add_u64 v[0:1], v[32:33], 0, s[12:13]
	global_load_dwordx4 v[12:15], v[0:1], off
	global_load_dwordx4 v[8:11], v[0:1], off offset:1024
	s_add_i32 s12, s22, 3
	v_readlane_b32 s12, v2, s12
	s_ashr_i32 s13, s12, 31
	s_lshl_b64 s[12:13], s[12:13], 11
	v_lshl_add_u64 v[0:1], v[32:33], 0, s[12:13]
	global_load_dwordx4 v[4:7], v[0:1], off
	s_nop 0
	global_load_dwordx4 v[0:3], v[0:1], off offset:1024
	s_waitcnt vmcnt(7)
	v_cvt_pk_f32_fp8_e32 v[98:99], v94
	v_cvt_pk_f32_fp8_sdwa v[100:101], v94 src0_sel:WORD_1
	v_fma_f32 v102, v52, v98, 0
	v_fmac_f32_e32 v102, v53, v99
	v_cvt_pk_f32_fp8_e32 v[98:99], v95
	v_cvt_pk_f32_fp8_sdwa v[94:95], v95 src0_sel:WORD_1
	v_fmac_f32_e32 v102, v63, v100
	v_fmac_f32_e32 v102, v64, v101
	v_fma_f32 v100, v65, v98, 0
	v_fmac_f32_e32 v100, v66, v99
	v_fmac_f32_e32 v100, v67, v94
	v_fmac_f32_e32 v100, v68, v95
	v_cvt_pk_f32_fp8_e32 v[94:95], v96
	v_cvt_pk_f32_fp8_sdwa v[98:99], v96 src0_sel:WORD_1
	v_fmac_f32_e32 v102, v69, v94
	v_fmac_f32_e32 v102, v70, v95
	v_cvt_pk_f32_fp8_e32 v[94:95], v97
	v_fmac_f32_e32 v102, v71, v98
	v_cvt_pk_f32_fp8_sdwa v[96:97], v97 src0_sel:WORD_1
	v_fmac_f32_e32 v102, v72, v99
	v_fmac_f32_e32 v100, v73, v94
	v_fmac_f32_e32 v100, v74, v95
	s_waitcnt vmcnt(6)
	v_cvt_pk_f32_fp8_e32 v[94:95], v24
	v_fmac_f32_e32 v100, v75, v96
	v_fmac_f32_e32 v100, v76, v97
	v_cvt_pk_f32_fp8_sdwa v[96:97], v24 src0_sel:WORD_1
	v_fmac_f32_e32 v102, v77, v94
	v_fmac_f32_e32 v102, v78, v95
	v_cvt_pk_f32_fp8_e32 v[94:95], v25
	v_cvt_pk_f32_fp8_sdwa v[24:25], v25 src0_sel:WORD_1
	v_fmac_f32_e32 v102, v79, v96
	v_fmac_f32_e32 v102, v80, v97
	v_fmac_f32_e32 v100, v81, v94
	v_fmac_f32_e32 v100, v82, v95
	v_fmac_f32_e32 v100, v83, v24
	v_fmac_f32_e32 v100, v84, v25
	v_cvt_pk_f32_fp8_e32 v[24:25], v26
	v_cvt_pk_f32_fp8_sdwa v[94:95], v26 src0_sel:WORD_1
	v_fmac_f32_e32 v102, v85, v24
	v_fmac_f32_e32 v102, v86, v25
	v_cvt_pk_f32_fp8_e32 v[24:25], v27
	v_cvt_pk_f32_fp8_sdwa v[26:27], v27 src0_sel:WORD_1
	v_fmac_f32_e32 v102, v87, v94
	v_fmac_f32_e32 v102, v88, v95
	v_fmac_f32_e32 v100, v89, v24
	v_fmac_f32_e32 v100, v90, v25
	v_fmac_f32_e32 v100, v91, v26
	v_fmac_f32_e32 v100, v92, v27
	s_waitcnt vmcnt(5)
	v_cvt_pk_f32_fp8_e32 v[26:27], v20
	v_cvt_pk_f32_fp8_sdwa v[94:95], v20 src0_sel:WORD_1
	v_add_f32_e32 v24, v102, v100
	v_fma_f32 v25, v52, v26, 0
	v_fmac_f32_e32 v25, v53, v27
	v_cvt_pk_f32_fp8_e32 v[26:27], v21
	v_cvt_pk_f32_fp8_sdwa v[20:21], v21 src0_sel:WORD_1
	v_fmac_f32_e32 v25, v63, v94
	v_fmac_f32_e32 v25, v64, v95
	v_fma_f32 v94, v65, v26, 0
	v_fmac_f32_e32 v94, v66, v27
	v_fmac_f32_e32 v94, v67, v20
	v_fmac_f32_e32 v94, v68, v21
	v_cvt_pk_f32_fp8_e32 v[20:21], v22
	v_cvt_pk_f32_fp8_sdwa v[26:27], v22 src0_sel:WORD_1
	v_fmac_f32_e32 v25, v69, v20
	v_fmac_f32_e32 v25, v70, v21
	v_cvt_pk_f32_fp8_e32 v[20:21], v23
	v_fmac_f32_e32 v25, v71, v26
	v_cvt_pk_f32_fp8_sdwa v[22:23], v23 src0_sel:WORD_1
	v_fmac_f32_e32 v25, v72, v27
	v_fmac_f32_e32 v94, v73, v20
	v_fmac_f32_e32 v94, v74, v21
	s_waitcnt vmcnt(4)
	v_cvt_pk_f32_fp8_e32 v[20:21], v16
	v_fmac_f32_e32 v94, v75, v22
	v_fmac_f32_e32 v94, v76, v23
	v_cvt_pk_f32_fp8_sdwa v[22:23], v16 src0_sel:WORD_1
	v_fmac_f32_e32 v25, v77, v20
	v_fmac_f32_e32 v25, v78, v21
	v_cvt_pk_f32_fp8_e32 v[20:21], v17
	v_cvt_pk_f32_fp8_sdwa v[16:17], v17 src0_sel:WORD_1
	v_fmac_f32_e32 v25, v79, v22
	v_fmac_f32_e32 v25, v80, v23
	v_fmac_f32_e32 v94, v81, v20
	v_fmac_f32_e32 v94, v82, v21
	v_fmac_f32_e32 v94, v83, v16
	v_fmac_f32_e32 v94, v84, v17
	v_cvt_pk_f32_fp8_e32 v[16:17], v18
	v_cvt_pk_f32_fp8_sdwa v[20:21], v18 src0_sel:WORD_1
	v_fmac_f32_e32 v25, v85, v16
	v_fmac_f32_e32 v25, v86, v17
	v_cvt_pk_f32_fp8_e32 v[16:17], v19
	v_cvt_pk_f32_fp8_sdwa v[18:19], v19 src0_sel:WORD_1
	v_fmac_f32_e32 v25, v87, v20
	v_fmac_f32_e32 v25, v88, v21
	v_fmac_f32_e32 v94, v89, v16
	v_fmac_f32_e32 v94, v90, v17
	s_waitcnt vmcnt(3)
; template <int MASK>
; __global__ void __launch_bounds__(256, 2) fwd_megakernel_t(Params p) {
;     ...
;           float a[4];
; #pragma unroll
;           for (int e = 0; e < 4; e++) {
;             float s0 = 0.f, s1 = 0.f;
;             s0 = dot4_fp8(r[e][0].x, xn[0], xn[1], xn[2], xn[3], s0);
;             s1 = dot4_fp8(r[e][0].y, xn[4], xn[5], xn[6], xn[7], s1);
;             s0 = dot4_fp8(r[e][0].z, xn[8], xn[9], xn[10], xn[11], s0);
;             s1 = dot4_fp8(r[e][0].w, xn[12], xn[13], xn[14], xn[15], s1);
;             s0 = dot4_fp8(r[e][1].x, xn[16], xn[17], xn[18], xn[19], s0);
;             s1 = dot4_fp8(r[e][1].y, xn[20], xn[21], xn[22], xn[23], s1);
;             s0 = dot4_fp8(r[e][1].z, xn[24], xn[25], xn[26], xn[27], s0);
;             s1 = dot4_fp8(r[e][1].w, xn[28], xn[29], xn[30], xn[31], s1);
;             a[e] = s0 + s1;
;           }
;           float c2[2], d;
;           {
;             const bool up = lane & 32;
; #pragma unroll
;             for (int i = 0; i < 2; i++) {
;               const float keep = up ? a[2 + i] : a[i], send = up ? a[i] : a[2 + i];
;               c2[i] = keep + __shfl_xor(send, 32);
;             }
;           }
;           {
;             const bool up = lane & 16;
;             const float keep = up ? c2[1] : c2[0], send = up ? c2[0] : c2[1];
;             d = keep + __shfl_xor(send, 16);
;           }
;           d += __shfl_xor(d, 8);
;           d += __shfl_xor(d, 4);
;           d += __shfl_xor(d, 2);
;           d += __shfl_xor(d, 1);
	v_cvt_pk_f32_fp8_e32 v[16:17], v12
	v_fmac_f32_e32 v94, v91, v18
	v_fmac_f32_e32 v94, v92, v19
	v_cvt_pk_f32_fp8_sdwa v[18:19], v12 src0_sel:WORD_1
	v_fma_f32 v21, v52, v16, 0
	v_fmac_f32_e32 v21, v53, v17
	v_cvt_pk_f32_fp8_e32 v[16:17], v13
	v_cvt_pk_f32_fp8_sdwa v[12:13], v13 src0_sel:WORD_1
	v_fmac_f32_e32 v21, v63, v18
	v_fmac_f32_e32 v21, v64, v19
	v_fma_f32 v18, v65, v16, 0
	v_fmac_f32_e32 v18, v66, v17
	v_fmac_f32_e32 v18, v67, v12
	v_fmac_f32_e32 v18, v68, v13
	v_cvt_pk_f32_fp8_e32 v[12:13], v14
	v_cvt_pk_f32_fp8_sdwa v[16:17], v14 src0_sel:WORD_1
	v_add_f32_e32 v20, v25, v94
	v_fmac_f32_e32 v21, v69, v12
	v_fmac_f32_e32 v21, v70, v13
	v_cvt_pk_f32_fp8_e32 v[12:13], v15
	v_fmac_f32_e32 v21, v71, v16
	v_cvt_pk_f32_fp8_sdwa v[14:15], v15 src0_sel:WORD_1
	v_fmac_f32_e32 v21, v72, v17
	v_fmac_f32_e32 v18, v73, v12
	v_fmac_f32_e32 v18, v74, v13
	s_waitcnt vmcnt(2)
	v_cvt_pk_f32_fp8_e32 v[12:13], v8
	v_fmac_f32_e32 v18, v75, v14
	v_fmac_f32_e32 v18, v76, v15
	v_cvt_pk_f32_fp8_sdwa v[14:15], v8 src0_sel:WORD_1
	v_fmac_f32_e32 v21, v77, v12
	v_fmac_f32_e32 v21, v78, v13
	v_cvt_pk_f32_fp8_e32 v[12:13], v9
	v_cvt_pk_f32_fp8_sdwa v[8:9], v9 src0_sel:WORD_1
	v_fmac_f32_e32 v21, v79, v14
	v_fmac_f32_e32 v21, v80, v15
	v_fmac_f32_e32 v18, v81, v12
	v_fmac_f32_e32 v18, v82, v13
	v_fmac_f32_e32 v18, v83, v8
	v_fmac_f32_e32 v18, v84, v9
	v_cvt_pk_f32_fp8_e32 v[8:9], v10
	v_cvt_pk_f32_fp8_sdwa v[12:13], v10 src0_sel:WORD_1
	v_fmac_f32_e32 v21, v85, v8
	v_fmac_f32_e32 v21, v86, v9
	v_cvt_pk_f32_fp8_e32 v[8:9], v11
	v_cvt_pk_f32_fp8_sdwa v[10:11], v11 src0_sel:WORD_1
	v_fmac_f32_e32 v21, v87, v12
	v_fmac_f32_e32 v21, v88, v13
	v_fmac_f32_e32 v18, v89, v8
	v_fmac_f32_e32 v18, v90, v9
	s_waitcnt vmcnt(1)
	v_cvt_pk_f32_fp8_e32 v[8:9], v4
	v_fmac_f32_e32 v18, v91, v10
	v_fmac_f32_e32 v18, v92, v11
	v_cvt_pk_f32_fp8_sdwa v[10:11], v4 src0_sel:WORD_1
	v_fma_f32 v13, v52, v8, 0
	v_fmac_f32_e32 v13, v53, v9
	v_cvt_pk_f32_fp8_e32 v[8:9], v5
	v_cvt_pk_f32_fp8_sdwa v[4:5], v5 src0_sel:WORD_1
	v_fmac_f32_e32 v13, v63, v10
	v_fmac_f32_e32 v13, v64, v11
	v_fma_f32 v10, v65, v8, 0
	v_fmac_f32_e32 v10, v66, v9
	v_fmac_f32_e32 v10, v67, v4
	v_fmac_f32_e32 v10, v68, v5
	v_cvt_pk_f32_fp8_e32 v[4:5], v6
	v_cvt_pk_f32_fp8_sdwa v[8:9], v6 src0_sel:WORD_1
	v_add_f32_e32 v12, v21, v18
	v_fmac_f32_e32 v13, v69, v4
	v_fmac_f32_e32 v13, v70, v5
	v_cvt_pk_f32_fp8_e32 v[4:5], v7
	v_fmac_f32_e32 v13, v71, v8
	v_cvt_pk_f32_fp8_sdwa v[6:7], v7 src0_sel:WORD_1
	v_fmac_f32_e32 v13, v72, v9
	v_fmac_f32_e32 v10, v73, v4
	v_fmac_f32_e32 v10, v74, v5
	s_waitcnt vmcnt(0)
	v_cvt_pk_f32_fp8_e32 v[4:5], v0
	v_fmac_f32_e32 v10, v75, v6
	v_fmac_f32_e32 v10, v76, v7
	v_cvt_pk_f32_fp8_sdwa v[6:7], v0 src0_sel:WORD_1
	v_fmac_f32_e32 v13, v77, v4
	v_fmac_f32_e32 v13, v78, v5
	v_cvt_pk_f32_fp8_e32 v[4:5], v1
	v_cvt_pk_f32_fp8_sdwa v[0:1], v1 src0_sel:WORD_1
	v_fmac_f32_e32 v13, v79, v6
	v_fmac_f32_e32 v13, v80, v7
	v_fmac_f32_e32 v10, v81, v4
	v_fmac_f32_e32 v10, v82, v5
	v_fmac_f32_e32 v10, v83, v0
	v_fmac_f32_e32 v10, v84, v1
	v_cvt_pk_f32_fp8_e32 v[0:1], v2
	v_cvt_pk_f32_fp8_sdwa v[4:5], v2 src0_sel:WORD_1
	v_fmac_f32_e32 v13, v85, v0
	v_fmac_f32_e32 v13, v86, v1
	v_cvt_pk_f32_fp8_e32 v[0:1], v3
	v_cvt_pk_f32_fp8_sdwa v[2:3], v3 src0_sel:WORD_1
	v_fmac_f32_e32 v13, v87, v4
	v_fmac_f32_e32 v13, v88, v5
	v_fmac_f32_e32 v10, v89, v0
	v_fmac_f32_e32 v10, v90, v1
	v_fmac_f32_e32 v10, v91, v2
	v_fmac_f32_e32 v10, v92, v3
	v_add_f32_e32 v0, v13, v10
	v_permlane32_swap_b32_e32 v24, v12
	v_add_f32_e32 v1, v24, v12
	v_permlane32_swap_b32_e32 v20, v0
	v_add_f32_e32 v0, v20, v0
	s_nop 1
	v_permlane16_swap_b32_e32 v1, v0
	v_add_f32_e32 v0, v1, v0
	s_nop 1
	v_add_f32_dpp v0, v0, v0 row_ror:8 row_mask:0xf bank_mask:0xf
	s_nop 1
	v_add_f32_dpp v0, v0, v0 row_ror:4 row_mask:0xf bank_mask:0xf
	s_nop 1
	v_add_f32_dpp v0, v0, v0 row_ror:2 row_mask:0xf bank_mask:0xf
	s_nop 1
	v_add_f32_dpp v0, v0, v0 row_ror:1 row_mask:0xf bank_mask:0xf
	s_and_saveexec_b64 s[12:13], s[8:9]
	ds_write_b32 v93, v0
	s_branch .LBB0_36
